# attention second half: 12 of 16 next-tile p0 exps issued speculatively in PV MFMA gaps (recomputed on the rare subtract path)
# baseline (speedup 1.0000x reference)
; template <bool FIRST>
; __device__ __forceinline__ void partialSM(f32x16& p0, f32x16& p1, float& m_reg, float& mn, float& alpha) {
;     ...
;     for (int r = 0; r < 16; ++r) p0[r] = __builtin_amdgcn_exp2f(p0[r]);
; __device__ __forceinline__ void qkt(f32x16& p0, f32x16& p1, const char* Kn, const bf16x8* qr, int r32, int hi) {
;     const char* Kr = Kn + KR_OFF;
;     p0 = f32x16{}; p1 = f32x16{};
;     __builtin_amdgcn_s_setprio(1);
; #pragma unroll
;     for (int d0 = 0; d0 < 8; ++d0) { const int cb = (d0 * 16 + hi * 8) * 2;
;         const bf16x8 b0 = *reinterpret_cast<const bf16x8*>(Kn + KNSWZ(r32, cb));
;         const bf16x8 b1 = *reinterpret_cast<const bf16x8*>(Kn + KNSWZ(32 + r32, cb));
;         p0 = __builtin_amdgcn_mfma_f32_32x32x16_bf16(b0, qr[d0], p0, 0, 0, 0);
;         p1 = __builtin_amdgcn_mfma_f32_32x32x16_bf16(b1, qr[d0], p1, 0, 0, 0); }
; #pragma unroll
;     for (int d0 = 0; d0 < 4; ++d0) { const int cb = (d0 * 16 + hi * 8) * 2;
;         const bf16x8 b0 = *reinterpret_cast<const bf16x8*>(Kr + KRSWZ(r32, cb));
;         const bf16x8 b1 = *reinterpret_cast<const bf16x8*>(Kr + KRSWZ(32 + r32, cb));
;         p0 = __builtin_amdgcn_mfma_f32_32x32x16_bf16(b0, qr[8 + d0], p0, 0, 0, 0);
;         p1 = __builtin_amdgcn_mfma_f32_32x32x16_bf16(b1, qr[8 + d0], p1, 0, 0, 0); }
; }
.LBB0_221:
	v_exp_f32_e32 v182, v98
	v_exp_f32_e32 v172, v96
	v_exp_f32_e32 v173, v97
	v_exp_f32_e32 v195, v99
	v_exp_f32_e32 v196, v100
	v_exp_f32_e32 v197, v101
	v_exp_f32_e32 v198, v102
	v_exp_f32_e32 v199, v103
	v_exp_f32_e32 v200, v104
	v_exp_f32_e32 v234, v105
	v_exp_f32_e32 v235, v106
	v_exp_f32_e32 v236, v107
	v_exp_f32_e32 v237, v108
	v_exp_f32_e32 v238, v109
	v_exp_f32_e32 v239, v110
	v_exp_f32_e32 v240, v111
	s_mul_i32 s0, s10, 0x6000
	s_add_i32 s16, s0, 0
	s_add_i32 s17, s16, s6
	s_add_i32 s18, s16, s8
	s_waitcnt vmcnt(0) lgkmcnt(0)
	s_barrier
	s_add_i32 s15, s7, s15
	s_setprio 1
	v_add_u32_e32 v68, s14, v207
	ds_read_b128 v[64:67], v68
	ds_read_b128 v[68:71], v68 offset:8192
	v_add_u32_e32 v186, s14, v210
	ds_read_b128 v[168:171], v186
	ds_read_b128 v[186:189], v186 offset:8192
	s_waitcnt lgkmcnt(0)
	v_mfma_f32_32x32x16_bf16 v[96:111], v[64:67], v[156:159], 0
	v_mfma_f32_32x32x16_bf16 v[64:79], v[68:71], v[156:159], 0
	v_mfma_f32_32x32x16_bf16 v[96:111], v[168:171], v[152:155], v[96:111]
	v_mfma_f32_32x32x16_bf16 v[64:79], v[186:189], v[152:155], v[64:79]
	v_add_u32_e32 v186, s14, v218
	ds_read_b128 v[168:171], v186
	ds_read_b128 v[186:189], v186 offset:8192
	s_mov_b32 m0, s17
	s_add_u32 s100, s72, 0x26580000
	s_addc_u32 s101, s73, 0
	global_load_lds_dwordx4 v178, s[100:101]
	s_waitcnt lgkmcnt(0)
	v_mfma_f32_32x32x16_bf16 v[96:111], v[168:171], v[148:151], v[96:111]
	v_mfma_f32_32x32x16_bf16 v[64:79], v[186:189], v[148:151], v[64:79]
	v_add_u32_e32 v186, s14, v221
	ds_read_b128 v[168:171], v186
	ds_read_b128 v[186:189], v186 offset:8192
	s_waitcnt lgkmcnt(0)
	v_mfma_f32_32x32x16_bf16 v[96:111], v[168:171], v[144:147], v[96:111]
	v_mfma_f32_32x32x16_bf16 v[64:79], v[186:189], v[144:147], v[64:79]
	v_add_u32_e32 v186, s14, v222
	ds_read_b128 v[168:171], v186
	ds_read_b128 v[186:189], v186 offset:8192
	s_add_i32 m0, s17, 0x400
	s_nop 0
	global_load_lds_dwordx4 v180, s[100:101]
	v_exp_f32_e32 v190, v88
	s_waitcnt lgkmcnt(0)
	v_mfma_f32_32x32x16_bf16 v[96:111], v[168:171], v[140:143], v[96:111]
	v_mfma_f32_32x32x16_bf16 v[64:79], v[186:189], v[140:143], v[64:79]
	v_add_u32_e32 v186, s14, v223
	ds_read_b128 v[168:171], v186
	ds_read_b128 v[186:189], v186 offset:8192
	v_exp_f32_e32 v191, v89
	s_waitcnt lgkmcnt(0)
	v_mfma_f32_32x32x16_bf16 v[96:111], v[168:171], v[136:139], v[96:111]
	v_mfma_f32_32x32x16_bf16 v[64:79], v[186:189], v[136:139], v[64:79]
	v_add_u32_e32 v186, s14, v224
	ds_read_b128 v[168:171], v186
	ds_read_b128 v[186:189], v186 offset:8192
	s_mov_b32 m0, s15
	s_add_u32 s100, s72, 0x26580100
	s_addc_u32 s101, s73, 0
	global_load_lds_dwordx4 v176, s[100:101]
	v_exp_f32_e32 v192, v90
	s_waitcnt lgkmcnt(0)
	v_mfma_f32_32x32x16_bf16 v[96:111], v[168:171], v[132:135], v[96:111]
	v_mfma_f32_32x32x16_bf16 v[64:79], v[186:189], v[132:135], v[64:79]
	v_add_u32_e32 v186, s14, v225
	ds_read_b128 v[168:171], v186
	ds_read_b128 v[186:189], v186 offset:8192
	v_exp_f32_e32 v193, v91
	s_waitcnt lgkmcnt(0)
	v_mfma_f32_32x32x16_bf16 v[96:111], v[168:171], v[128:131], v[96:111]
	v_mfma_f32_32x32x16_bf16 v[64:79], v[186:189], v[128:131], v[64:79]
	v_add_u32_e32 v186, s14, v226
	ds_read_b128 v[168:171], v186 offset:16384
	ds_read_b128 v[186:189], v186 offset:20480
	s_add_i32 m0, s15, 0x400
	s_add_u32 s100, s72, 0x26580180
	s_addc_u32 s101, s73, 0
	global_load_lds_dwordx4 v176, s[100:101]
	v_exp_f32_e32 v241, v92
	s_waitcnt lgkmcnt(0)
	v_mfma_f32_32x32x16_bf16 v[96:111], v[168:171], v[124:127], v[96:111]
	v_mfma_f32_32x32x16_bf16 v[64:79], v[186:189], v[124:127], v[64:79]
	v_add_u32_e32 v186, s14, v227
	ds_read_b128 v[168:171], v186 offset:16384
	ds_read_b128 v[186:189], v186 offset:20480
	v_exp_f32_e32 v242, v93
	s_waitcnt lgkmcnt(0)
	v_mfma_f32_32x32x16_bf16 v[96:111], v[168:171], v[120:123], v[96:111]
	v_mfma_f32_32x32x16_bf16 v[64:79], v[186:189], v[120:123], v[64:79]
	v_add_u32_e32 v186, s14, v228
	ds_read_b128 v[168:171], v186 offset:16384
	ds_read_b128 v[186:189], v186 offset:20480
	s_add_i32 m0, s18, 0x4000
	s_add_u32 s100, s72, 0x21206000
	s_addc_u32 s101, s73, 0
	global_load_lds_dwordx4 v174, s[100:101]
	v_exp_f32_e32 v94, v94
	s_waitcnt lgkmcnt(0)
	v_mfma_f32_32x32x16_bf16 v[96:111], v[168:171], v[116:119], v[96:111]
	v_mfma_f32_32x32x16_bf16 v[64:79], v[186:189], v[116:119], v[64:79]
	v_add_u32_e32 v186, s14, v229
	ds_read_b128 v[168:171], v186 offset:16384
	ds_read_b128 v[186:189], v186 offset:20480
	v_exp_f32_e32 v95, v95
	s_waitcnt lgkmcnt(0)
; #define SBAR() __builtin_amdgcn_sched_barrier(0)
; template <bool FIRST>
; __device__ __forceinline__ void partialSM(f32x16& p0, f32x16& p1, float& m_reg, float& mn, float& alpha) {
;     ...
;         for (int r = 0; r < 16; ++r) p0[r] = p0[r] - mn;
; #pragma unroll
;         for (int r = 0; r < 16; ++r) p1[r] = p1[r] - mn; }
; #pragma unroll
;     for (int r = 0; r < 16; ++r) p0[r] = __builtin_amdgcn_exp2f(p0[r]);
; template <int D0> __device__ __forceinline__ void pv_one(f32x16& od, int vb, bf16x8 pa0, bf16x8 pa1, bf16x8 pa2, bf16x8 pa3) {
;     const s16x4 l0 = tr_read<v_rd_off(D0, 0, 0)>(vb), h0 = tr_read<v_rd_off(D0, 0, 1)>(vb), l1 = tr_read<v_rd_off(D0, 1, 0)>(vb), h1 = tr_read<v_rd_off(D0, 1, 1)>(vb);
;     const s16x4 l2 = tr_read<v_rd_off(D0, 2, 0)>(vb), h2 = tr_read<v_rd_off(D0, 2, 1)>(vb), l3 = tr_read<v_rd_off(D0, 3, 0)>(vb), h3 = tr_read<v_rd_off(D0, 3, 1)>(vb);
;     asm volatile("s_waitcnt lgkmcnt(0)" ::: "memory"); SBAR();
;     ...
;     od = __builtin_amdgcn_mfma_f32_32x32x16_bf16(pa0, PK(l0, h0), od, 0, 0, 0);
;     od = __builtin_amdgcn_mfma_f32_32x32x16_bf16(pa1, PK(l1, h1), od, 0, 0, 0);
;     od = __builtin_amdgcn_mfma_f32_32x32x16_bf16(pa2, PK(l2, h2), od, 0, 0, 0);
;     od = __builtin_amdgcn_mfma_f32_32x32x16_bf16(pa3, PK(l3, h3), od, 0, 0, 0);
;     ...
; }
; __device__ __forceinline__ void pv_d0(f32x16* o, int vb, bf16x8 pa0, bf16x8 pa1, bf16x8 pa2, bf16x8 pa3) {
;     pv_one<0>(o[0], vb, pa0, pa1, pa2, pa3); pv_one<1>(o[1], vb, pa0, pa1, pa2, pa3); pv_one<2>(o[2], vb, pa0, pa1, pa2, pa3); pv_one<3>(o[3], vb, pa0, pa1, pa2, pa3);
	v_mfma_f32_32x32x16_bf16 v[96:111], v[168:171], v[112:115], v[96:111]
	v_exp_f32_e32 v168, v80
	v_add_f32_e32 v80, 0, v172
	v_add_f32_e32 v80, v173, v80
	v_add_f32_e32 v80, v182, v80
	v_add_f32_e32 v80, v195, v80
	v_add_f32_e32 v80, v196, v80
	v_add_f32_e32 v80, v197, v80
	v_add_f32_e32 v80, v198, v80
	v_add_f32_e32 v80, v199, v80
	v_add_f32_e32 v80, v200, v80
	v_add_f32_e32 v80, v234, v80
	v_add_f32_e32 v80, v235, v80
	v_add_f32_e32 v80, v236, v80
	v_add_f32_e32 v80, v237, v80
	v_exp_f32_e32 v169, v81
	v_add_f32_e32 v80, v238, v80
	v_exp_f32_e32 v170, v82
	v_add_f32_e32 v80, v239, v80
	v_exp_f32_e32 v171, v83
	v_add_f32_e32 v80, v240, v80
	v_mfma_f32_32x32x16_bf16 v[64:79], v[186:189], v[112:115], v[64:79]
	v_exp_f32_e32 v186, v84
	v_add_f32_e32 v80, v168, v80
	v_exp_f32_e32 v187, v85
	v_add_f32_e32 v80, v169, v80
	v_exp_f32_e32 v188, v86
	v_add_f32_e32 v80, v170, v80
	v_exp_f32_e32 v189, v87
	v_add_f32_e32 v80, v171, v80
	v_add_f32_e32 v80, v186, v80
	v_add_f32_e32 v80, v187, v80
	v_add_f32_e32 v80, v188, v80
	v_add_f32_e32 v80, v189, v80
	v_add_f32_e32 v80, v190, v80
	v_add_f32_e32 v80, v191, v80
	v_add_f32_e32 v80, v192, v80
	v_add_f32_e32 v80, v193, v80
	v_add_f32_e32 v80, v241, v80
	v_add_f32_e32 v80, v242, v80
	v_add_f32_e32 v80, v94, v80
	v_add_f32_e32 v80, v95, v80
	v_mov_b32_e32 v81, v80
	v_cvt_pk_bf16_f32 v82, v172, v173
	v_cvt_pk_bf16_f32 v83, v182, v195
	v_cvt_pk_bf16_f32 v84, v196, v197
	s_nop 1
	v_permlane32_swap_b32_e32 v80, v81
	v_cvt_pk_bf16_f32 v85, v198, v199
	v_permlane32_swap_b32_e32 v82, v84
	v_cvt_pk_bf16_f32 v86, v200, v234
	v_cvt_pk_bf16_f32 v87, v235, v236
	v_cvt_pk_bf16_f32 v88, v237, v238
	v_cvt_pk_bf16_f32 v89, v239, v240
	v_cvt_pk_bf16_f32 v90, v168, v169
	v_cvt_pk_bf16_f32 v91, v170, v171
	v_cvt_pk_bf16_f32 v92, v186, v187
	v_cvt_pk_bf16_f32 v93, v188, v189
	v_cvt_pk_bf16_f32 v168, v190, v191
	v_cvt_pk_bf16_f32 v169, v192, v193
	v_cvt_pk_bf16_f32 v170, v241, v242
	v_cvt_pk_bf16_f32 v171, v94, v95
	v_permlane32_swap_b32_e32 v83, v85
	v_permlane32_swap_b32_e32 v86, v88
	v_permlane32_swap_b32_e32 v87, v89
	v_permlane32_swap_b32_e32 v90, v92
	v_permlane32_swap_b32_e32 v91, v93
	v_permlane32_swap_b32_e32 v168, v170
	v_permlane32_swap_b32_e32 v169, v171
	s_setprio 0
	v_lshl_add_u32 v94, s13, 14, v205
	ds_read_b64_tr_b16 v[186:187], v94 offset:0
	ds_read_b64_tr_b16 v[188:189], v94 offset:0x800
	ds_read_b64_tr_b16 v[190:191], v94 offset:0x1000
	ds_read_b64_tr_b16 v[192:193], v94 offset:0x1800
	ds_read_b64_tr_b16 v[196:197], v94 offset:0x2000
	ds_read_b64_tr_b16 v[198:199], v94 offset:0x2800
	ds_read_b64_tr_b16 v[234:235], v94 offset:0x3000
	ds_read_b64_tr_b16 v[236:237], v94 offset:0x3800
	s_waitcnt lgkmcnt(0)
	s_nop 0
	v_mfma_f32_32x32x16_bf16 v[0:15], v[82:85], v[186:189], v[0:15]
	ds_read_b64_tr_b16 v[186:187], v94 offset:0x200
	ds_read_b64_tr_b16 v[188:189], v94 offset:0xa00
	v_exp_f32_e32 v247, v96
	v_mfma_f32_32x32x16_bf16 v[0:15], v[86:89], v[190:193], v[0:15]
	ds_read_b64_tr_b16 v[190:191], v94 offset:0x1200
	ds_read_b64_tr_b16 v[192:193], v94 offset:0x1a00
	v_exp_f32_e32 v249, v97
	v_mfma_f32_32x32x16_bf16 v[0:15], v[90:93], v[196:199], v[0:15]
	ds_read_b64_tr_b16 v[196:197], v94 offset:0x2200
	ds_read_b64_tr_b16 v[198:199], v94 offset:0x2a00
	v_exp_f32_e32 v245, v98
	v_mfma_f32_32x32x16_bf16 v[0:15], v[168:171], v[234:237], v[0:15]
	ds_read_b64_tr_b16 v[234:235], v94 offset:0x3200
	ds_read_b64_tr_b16 v[236:237], v94 offset:0x3a00
	v_exp_f32_e32 v248, v99
	s_waitcnt lgkmcnt(0)
	v_mfma_f32_32x32x16_bf16 v[48:63], v[82:85], v[186:189], v[48:63]
	ds_read_b64_tr_b16 v[186:187], v94 offset:0x400
	ds_read_b64_tr_b16 v[188:189], v94 offset:0xc00
	v_exp_f32_e32 v244, v100
	v_mfma_f32_32x32x16_bf16 v[48:63], v[86:89], v[190:193], v[48:63]
	ds_read_b64_tr_b16 v[190:191], v94 offset:0x1400
	ds_read_b64_tr_b16 v[192:193], v94 offset:0x1c00
	v_exp_f32_e32 v246, v101
	v_mfma_f32_32x32x16_bf16 v[48:63], v[90:93], v[196:199], v[48:63]
	ds_read_b64_tr_b16 v[196:197], v94 offset:0x2400
	ds_read_b64_tr_b16 v[198:199], v94 offset:0x2c00
	v_exp_f32_e32 v242, v102
	v_mfma_f32_32x32x16_bf16 v[48:63], v[168:171], v[234:237], v[48:63]
	ds_read_b64_tr_b16 v[234:235], v94 offset:0x3400
	ds_read_b64_tr_b16 v[236:237], v94 offset:0x3c00
	v_exp_f32_e32 v243, v103
	s_waitcnt lgkmcnt(0)
	v_mfma_f32_32x32x16_bf16 v[32:47], v[82:85], v[186:189], v[32:47]
	ds_read_b64_tr_b16 v[186:187], v94 offset:0x600
	ds_read_b64_tr_b16 v[188:189], v94 offset:0xe00
	v_exp_f32_e32 v239, v104
	v_mfma_f32_32x32x16_bf16 v[32:47], v[86:89], v[190:193], v[32:47]
	ds_read_b64_tr_b16 v[190:191], v94 offset:0x1600
	ds_read_b64_tr_b16 v[192:193], v94 offset:0x1e00
	v_exp_f32_e32 v241, v105
	v_mfma_f32_32x32x16_bf16 v[32:47], v[90:93], v[196:199], v[32:47]
	ds_read_b64_tr_b16 v[196:197], v94 offset:0x2600
	ds_read_b64_tr_b16 v[198:199], v94 offset:0x2e00
	v_exp_f32_e32 v238, v106
	v_mfma_f32_32x32x16_bf16 v[32:47], v[168:171], v[234:237], v[32:47]
	ds_read_b64_tr_b16 v[234:235], v94 offset:0x3600
	ds_read_b64_tr_b16 v[236:237], v94 offset:0x3e00
	v_exp_f32_e32 v240, v107
	s_waitcnt lgkmcnt(0)
	v_mfma_f32_32x32x16_bf16 v[16:31], v[82:85], v[186:189], v[16:31]
	v_max_f32_e32 v82, v97, v97
	v_max_f32_e32 v83, v96, v96
	v_max_f32_e32 v82, v83, v82
	v_max3_f32 v82, v82, v98, v99
	v_max3_f32 v82, v82, v100, v101
	v_max3_f32 v82, v82, v102, v103
	v_max3_f32 v82, v82, v104, v105
	v_mfma_f32_32x32x16_bf16 v[16:31], v[86:89], v[190:193], v[16:31]
	v_max3_f32 v82, v82, v106, v107
	v_max3_f32 v82, v82, v108, v109
	v_max3_f32 v82, v82, v110, v111
	v_max3_f32 v82, v82, v64, v65
	v_max3_f32 v82, v82, v66, v67
	v_max3_f32 v82, v82, v68, v69
	v_max3_f32 v82, v82, v70, v71
	v_mfma_f32_32x32x16_bf16 v[16:31], v[90:93], v[196:199], v[16:31]
	v_max3_f32 v82, v82, v72, v73
	v_max3_f32 v82, v82, v74, v75
	v_max3_f32 v82, v82, v76, v77
	v_max3_f32 v82, v82, v78, v79
	v_mov_b32_e32 v83, v82
	s_nop 1
	v_permlane32_swap_b32_e32 v82, v83
	v_max_f32_e32 v83, v83, v83
	v_max_f32_e32 v82, v82, v82
	v_mfma_f32_32x32x16_bf16 v[16:31], v[168:171], v[234:237], v[16:31]
	v_max_f32_e32 v82, v82, v83
	v_sub_f32_e32 v83, v82, v184
	s_mov_b32 s0, 0x41300000
	v_cmp_ge_f32_e32 vcc, s0, v83
	v_mov_b32_e32 v182, v184
	s_cmp_eq_u64 vcc, exec
	s_cbranch_scc0 .Latt_slow2
	s_cmp_lg_u32 s19, 0
	s_cbranch_scc0 .LBB0_229
	v_mov_b32_e32 v184, 1.0
.LBB0_226:
	v_exp_f32_e32 v235, v108
	v_exp_f32_e32 v237, v109
	v_exp_f32_e32 v234, v110
	v_exp_f32_e32 v236, v111
	v_add_f32_e32 v82, v231, v232
	s_mov_b64 s[0:1], 0x4000
	v_fmac_f32_e32 v82, v230, v203
	v_add_f32_e32 v203, v80, v81
	s_add_i32 s11, s11, 2
	v_lshl_add_u64 v[174:175], v[174:175], 0, s[0:1]
	s_mov_b64 s[0:1], 0x100000
	v_fmac_f32_e32 v203, v82, v233
	v_lshl_add_u64 v[176:177], v[176:177], 0, s[0:1]
	v_lshl_add_u64 v[178:179], v[178:179], 0, s[0:1]
	v_lshl_add_u64 v[180:181], v[180:181], 0, s[0:1]
	v_mov_b32_e32 v230, v184
	s_waitcnt vmcnt(0) lgkmcnt(0)
	s_barrier
	s_cmpk_gt_u32 s11, 0x7c
	s_cbranch_scc1 .LBB0_230
	s_mov_b32 s15, s9
	s_mov_b32 s9, s13
	s_branch .LBB0_216

; template <bool FIRST>
; __device__ __forceinline__ void partialSM(f32x16& p0, f32x16& p1, float& m_reg, float& mn, float& alpha) {
;     ...
;     if (!__builtin_expect(__all(mn == 0.f), 1)) {
; #pragma unroll
;         for (int r = 0; r < 16; ++r) p0[r] = p0[r] - mn;
; #pragma unroll
;         for (int r = 0; r < 16; ++r) p1[r] = p1[r] - mn; }
; #pragma unroll
;     for (int r = 0; r < 16; ++r) p0[r] = __builtin_amdgcn_exp2f(p0[r]);
.LBB0_229:
	v_pk_add_f32 v[96:97], v[96:97], v[182:183] op_sel_hi:[1,0] neg_lo:[0,1] neg_hi:[0,1]
	v_pk_add_f32 v[98:99], v[98:99], v[182:183] op_sel_hi:[1,0] neg_lo:[0,1] neg_hi:[0,1]
	v_pk_add_f32 v[100:101], v[100:101], v[182:183] op_sel_hi:[1,0] neg_lo:[0,1] neg_hi:[0,1]
	v_pk_add_f32 v[102:103], v[102:103], v[182:183] op_sel_hi:[1,0] neg_lo:[0,1] neg_hi:[0,1]
	v_pk_add_f32 v[104:105], v[104:105], v[182:183] op_sel_hi:[1,0] neg_lo:[0,1] neg_hi:[0,1]
	v_pk_add_f32 v[106:107], v[106:107], v[182:183] op_sel_hi:[1,0] neg_lo:[0,1] neg_hi:[0,1]
	v_pk_add_f32 v[108:109], v[108:109], v[182:183] op_sel_hi:[1,0] neg_lo:[0,1] neg_hi:[0,1]
	v_pk_add_f32 v[110:111], v[110:111], v[182:183] op_sel_hi:[1,0] neg_lo:[0,1] neg_hi:[0,1]
	v_sub_f32_e32 v79, v79, v182
	v_sub_f32_e32 v78, v78, v182
	v_sub_f32_e32 v77, v77, v182
	v_sub_f32_e32 v76, v76, v182
	v_sub_f32_e32 v75, v75, v182
	v_sub_f32_e32 v74, v74, v182
	v_sub_f32_e32 v73, v73, v182
	v_sub_f32_e32 v72, v72, v182
	v_sub_f32_e32 v71, v71, v182
	v_sub_f32_e32 v70, v70, v182
	v_sub_f32_e32 v69, v69, v182
	v_sub_f32_e32 v68, v68, v182
	v_sub_f32_e32 v67, v67, v182
	v_sub_f32_e32 v66, v66, v182
	v_sub_f32_e32 v65, v65, v182
	v_sub_f32_e32 v64, v64, v182
	v_exp_f32_e32 v247, v96
	v_exp_f32_e32 v249, v97
	v_exp_f32_e32 v245, v98
	v_exp_f32_e32 v248, v99
	v_exp_f32_e32 v244, v100
	v_exp_f32_e32 v246, v101
	v_exp_f32_e32 v242, v102
	v_exp_f32_e32 v243, v103
	v_exp_f32_e32 v239, v104
	v_exp_f32_e32 v241, v105
	v_exp_f32_e32 v238, v106
	v_exp_f32_e32 v240, v107
	s_branch .LBB0_222
